# sample-stream attention units: bias-table copy issues its 5 loads together; K/V cache lines of the unit touched once up front (L2 warm-up)
# baseline (speedup 1.0000x reference)
; __device__ __forceinline__ void attn_unit(LAS unsigned char* wl, const bf16* Qc, bf16* Oc, const bf16* KBc, const bf16* VBc, const bf16* CK, const bf16* CV, bool sample, int t0, const float* tabh, int lane, const int qh) {
;     ...
;     for (int i = lane; i < 257; i += 64) btab[i] = tabh[i];
;     const float cb = tabh[256];
;     bf16x8 qfr[4];
; #pragma unroll
;     for (int d0 = 0; d0 < 4; ++d0) qfr[d0] = *(const bf16x8*)(Qc + (size_t)(32 * qh + r32) * 1024 + 16 * d0 + 8 * hi);
;     ...
;     for (int t = t0; t < 9; ++t) {
;         const bf16 *kp, *vp;
;         if (sample && t < 8) { kp = CK + (size_t)t * 64 * 1024; vp = CV + (size_t)t * 64 * 1024; }
;         else { const long off = -(long)(8 - t) * 64 * 1024; kp = KBc + off; vp = VBc + off; }
;         u32x4 vreg[8];
; #pragma unroll
;         for (int i = 0; i < 8; ++i) vreg[i] = *(const u32x4*)(vp + (size_t)(8 * i + (lane >> 3)) * 1024 + (lane & 7) * 8);
.LBB0_512:
	global_load_dword v7, v[4:5], off
	global_load_dword v218, v[4:5], off offset:256
	global_load_dword v219, v[4:5], off offset:512
	global_load_dword v220, v[4:5], off offset:768
	v_cmp_eq_u32_e32 vcc, 0xffffffc0, v212
	s_and_saveexec_b64 s[30:31], vcc
	global_load_dword v221, v[4:5], off offset:1024
	s_mov_b64 exec, s[30:31]
	s_waitcnt vmcnt(1)
	ds_write_b32 v6, v7
	ds_write_b32 v6, v218 offset:256
	ds_write_b32 v6, v219 offset:512
	ds_write_b32 v6, v220 offset:768
	s_and_saveexec_b64 s[30:31], vcc
	s_waitcnt vmcnt(0)
	ds_write_b32 v6, v221 offset:1024
	s_mov_b64 exec, s[30:31]
	s_lshl_b32 s2, s3, 2
	v_mov_b32_e32 v2, s2
	v_lshl_add_u64 v[4:5], s[14:15], 1, v[146:147]
	global_load_dword v116, v2, s[28:29] offset:1024
	global_load_dwordx4 v[112:115], v[4:5], off
	global_load_dwordx4 v[108:111], v[4:5], off offset:32
	global_load_dwordx4 v[104:107], v[4:5], off offset:64
	global_load_dwordx4 v[100:103], v[4:5], off offset:96
	s_lshl_b64 s[6:7], s[4:5], 20
	v_mov_b32_e32 v124, 0
	v_lshl_add_u64 v[120:121], v[182:183], 0, s[6:7]
	v_lshl_add_u64 v[122:123], v[184:185], 0, s[6:7]
	v_mov_b32_e32 v2, 0xf149f2ca
	s_mov_b32 s2, 0
	s_mov_b32 s6, 0
	v_mov_b32_e32 v4, 0
	v_mov_b32_e32 v5, v124
	v_mov_b32_e32 v6, v124
	v_mov_b32_e32 v7, v124
	v_mov_b32_e32 v8, v124
	v_mov_b32_e32 v9, v124
	v_mov_b32_e32 v10, v124
	v_mov_b32_e32 v11, v124
	v_mov_b32_e32 v12, v124
	v_mov_b32_e32 v13, v124
	v_mov_b32_e32 v14, v124
	v_mov_b32_e32 v15, v124
	v_mov_b32_e32 v16, v124
	v_mov_b32_e32 v17, v124
	v_mov_b32_e32 v18, v124
	v_mov_b32_e32 v19, v124
	v_mov_b32_e32 v20, 0
	v_mov_b32_e32 v21, v124
	v_mov_b32_e32 v22, v124
	v_mov_b32_e32 v23, v124
	v_mov_b32_e32 v24, v124
	v_mov_b32_e32 v25, v124
	v_mov_b32_e32 v26, v124
	v_mov_b32_e32 v27, v124
	v_mov_b32_e32 v28, v124
	v_mov_b32_e32 v29, v124
	v_mov_b32_e32 v30, v124
	v_mov_b32_e32 v31, v124
	v_mov_b32_e32 v32, v124
	v_mov_b32_e32 v33, v124
	v_mov_b32_e32 v34, v124
	v_mov_b32_e32 v35, v124
	v_and_b32_e32 v238, 63, v212
	v_lshrrev_b32_e32 v239, 3, v238
	v_sub_u32_e32 v239, v238, v239
	v_and_b32_e32 v238, 7, v238
	v_lshlrev_b32_e32 v239, 11, v239
	v_lshlrev_b32_e32 v238, 4, v238
	v_sub_u32_e32 v238, v239, v238
	v_mov_b32_e32 v239, 0
	v_mov_b32_e32 v244, 0x20000
	v_mov_b32_e32 v245, 0
	v_lshl_add_u64 v[240:241], v[120:121], 0, v[238:239]
	v_lshl_add_u64 v[242:243], v[122:123], 0, v[238:239]
	v_lshl_add_u64 v[240:241], v[240:241], 0, s[78:79]
	v_lshl_add_u64 v[242:243], v[242:243], 0, s[78:79]
	global_load_dword v222, v[240:241], off
	global_load_dword v230, v[242:243], off
	v_lshl_add_u64 v[240:241], v[240:241], 0, v[244:245]
	v_lshl_add_u64 v[242:243], v[242:243], 0, v[244:245]
	global_load_dword v223, v[240:241], off
	global_load_dword v231, v[242:243], off
	v_lshl_add_u64 v[240:241], v[240:241], 0, v[244:245]
	v_lshl_add_u64 v[242:243], v[242:243], 0, v[244:245]
	global_load_dword v224, v[240:241], off
	global_load_dword v232, v[242:243], off
	v_lshl_add_u64 v[240:241], v[240:241], 0, v[244:245]
	v_lshl_add_u64 v[242:243], v[242:243], 0, v[244:245]
	global_load_dword v225, v[240:241], off
	global_load_dword v233, v[242:243], off
	v_lshl_add_u64 v[240:241], v[240:241], 0, v[244:245]
	v_lshl_add_u64 v[242:243], v[242:243], 0, v[244:245]
	global_load_dword v226, v[240:241], off
	global_load_dword v234, v[242:243], off
	v_lshl_add_u64 v[240:241], v[240:241], 0, v[244:245]
	v_lshl_add_u64 v[242:243], v[242:243], 0, v[244:245]
	global_load_dword v227, v[240:241], off
	global_load_dword v235, v[242:243], off
	v_lshl_add_u64 v[240:241], v[240:241], 0, v[244:245]
	v_lshl_add_u64 v[242:243], v[242:243], 0, v[244:245]
	global_load_dword v228, v[240:241], off
	global_load_dword v236, v[242:243], off
	v_lshl_add_u64 v[240:241], v[240:241], 0, v[244:245]
	v_lshl_add_u64 v[242:243], v[242:243], 0, v[244:245]
	global_load_dword v229, v[240:241], off
	global_load_dword v237, v[242:243], off
	s_waitcnt vmcnt(20)
	v_mov_b32_e32 v118, v116
	v_mov_b32_e32 v119, v116

; __device__ __forceinline__ void attn_unit(LAS unsigned char* wl, const bf16* Qc, bf16* Oc, const bf16* KBc, const bf16* VBc, const bf16* CK, const bf16* CV, bool sample, int t0, const float* tabh, int lane, const int qh) {
;     ...
;     for (int i = lane; i < 257; i += 64) btab[i] = tabh[i];
;     const float cb = tabh[256];
;     bf16x8 qfr[4];
; #pragma unroll
;     for (int d0 = 0; d0 < 4; ++d0) qfr[d0] = *(const bf16x8*)(Qc + (size_t)(32 * qh + r32) * 1024 + 16 * d0 + 8 * hi);
;     ...
;     for (int t = t0; t < 9; ++t) {
;         const bf16 *kp, *vp;
;         if (sample && t < 8) { kp = CK + (size_t)t * 64 * 1024; vp = CV + (size_t)t * 64 * 1024; }
;         else { const long off = -(long)(8 - t) * 64 * 1024; kp = KBc + off; vp = VBc + off; }
;         u32x4 vreg[8];
; #pragma unroll
;         for (int i = 0; i < 8; ++i) vreg[i] = *(const u32x4*)(vp + (size_t)(8 * i + (lane >> 3)) * 1024 + (lane & 7) * 8);
.LBB0_523:
	global_load_dword v7, v[4:5], off
	global_load_dword v218, v[4:5], off offset:256
	global_load_dword v219, v[4:5], off offset:512
	global_load_dword v220, v[4:5], off offset:768
	v_cmp_eq_u32_e32 vcc, 0xffffffc0, v212
	s_and_saveexec_b64 s[26:27], vcc
	global_load_dword v221, v[4:5], off offset:1024
	s_mov_b64 exec, s[26:27]
	s_waitcnt vmcnt(1)
	ds_write_b32 v6, v7
	ds_write_b32 v6, v218 offset:256
	ds_write_b32 v6, v219 offset:512
	ds_write_b32 v6, v220 offset:768
	s_and_saveexec_b64 s[26:27], vcc
	s_waitcnt vmcnt(0)
	ds_write_b32 v6, v221 offset:1024
	s_mov_b64 exec, s[26:27]
	s_lshl_b32 s2, s3, 2
	v_mov_b32_e32 v2, s2
	v_lshl_add_u64 v[4:5], s[14:15], 1, v[174:175]
	global_load_dword v116, v2, s[28:29] offset:1024
	global_load_dwordx4 v[112:115], v[4:5], off
	global_load_dwordx4 v[108:111], v[4:5], off offset:32
	global_load_dwordx4 v[104:107], v[4:5], off offset:64
	global_load_dwordx4 v[100:103], v[4:5], off offset:96
	s_lshl_b64 s[4:5], s[4:5], 20
	v_mov_b32_e32 v124, 0
	v_mov_b32_e32 v2, 0xf149f2ca
	s_mov_b32 s2, 0
	s_mov_b32 s3, 0
	v_mov_b32_e32 v4, 0
	v_mov_b32_e32 v20, 0
	v_lshl_add_u64 v[118:119], v[182:183], 0, s[4:5]
	v_lshl_add_u64 v[120:121], v[184:185], 0, s[4:5]
	v_mov_b32_e32 v5, v124
	v_mov_b32_e32 v6, v124
	v_mov_b32_e32 v7, v124
	v_mov_b32_e32 v8, v124
	v_mov_b32_e32 v9, v124
	v_mov_b32_e32 v10, v124
	v_mov_b32_e32 v11, v124
	v_mov_b32_e32 v12, v124
	v_mov_b32_e32 v13, v124
	v_mov_b32_e32 v14, v124
	v_mov_b32_e32 v15, v124
	v_mov_b32_e32 v16, v124
	v_mov_b32_e32 v17, v124
	v_mov_b32_e32 v18, v124
	v_mov_b32_e32 v19, v124
	v_mov_b32_e32 v21, v124
	v_mov_b32_e32 v22, v124
	v_mov_b32_e32 v23, v124
	v_mov_b32_e32 v24, v124
	v_mov_b32_e32 v25, v124
	v_mov_b32_e32 v26, v124
	v_mov_b32_e32 v27, v124
	v_mov_b32_e32 v28, v124
	v_mov_b32_e32 v29, v124
	v_mov_b32_e32 v30, v124
	v_mov_b32_e32 v31, v124
	v_mov_b32_e32 v32, v124
	v_mov_b32_e32 v33, v124
	v_mov_b32_e32 v34, v124
	v_mov_b32_e32 v35, v124
	v_and_b32_e32 v238, 63, v212
	v_lshrrev_b32_e32 v239, 3, v238
	v_sub_u32_e32 v239, v238, v239
	v_and_b32_e32 v238, 7, v238
	v_lshlrev_b32_e32 v239, 11, v239
	v_lshlrev_b32_e32 v238, 4, v238
	v_sub_u32_e32 v238, v239, v238
	v_mov_b32_e32 v239, 0
	v_mov_b32_e32 v244, 0x20000
	v_mov_b32_e32 v245, 0
	v_lshl_add_u64 v[240:241], v[118:119], 0, v[238:239]
	v_lshl_add_u64 v[242:243], v[120:121], 0, v[238:239]
	v_lshl_add_u64 v[240:241], v[240:241], 0, s[78:79]
	v_lshl_add_u64 v[242:243], v[242:243], 0, s[78:79]
	global_load_dword v222, v[240:241], off
	global_load_dword v230, v[242:243], off
	v_lshl_add_u64 v[240:241], v[240:241], 0, v[244:245]
	v_lshl_add_u64 v[242:243], v[242:243], 0, v[244:245]
	global_load_dword v223, v[240:241], off
	global_load_dword v231, v[242:243], off
	v_lshl_add_u64 v[240:241], v[240:241], 0, v[244:245]
	v_lshl_add_u64 v[242:243], v[242:243], 0, v[244:245]
	global_load_dword v224, v[240:241], off
	global_load_dword v232, v[242:243], off
	v_lshl_add_u64 v[240:241], v[240:241], 0, v[244:245]
	v_lshl_add_u64 v[242:243], v[242:243], 0, v[244:245]
	global_load_dword v225, v[240:241], off
	global_load_dword v233, v[242:243], off
	v_lshl_add_u64 v[240:241], v[240:241], 0, v[244:245]
	v_lshl_add_u64 v[242:243], v[242:243], 0, v[244:245]
	global_load_dword v226, v[240:241], off
	global_load_dword v234, v[242:243], off
	v_lshl_add_u64 v[240:241], v[240:241], 0, v[244:245]
	v_lshl_add_u64 v[242:243], v[242:243], 0, v[244:245]
	global_load_dword v227, v[240:241], off
	global_load_dword v235, v[242:243], off
	v_lshl_add_u64 v[240:241], v[240:241], 0, v[244:245]
	v_lshl_add_u64 v[242:243], v[242:243], 0, v[244:245]
	global_load_dword v228, v[240:241], off
	global_load_dword v236, v[242:243], off
	v_lshl_add_u64 v[240:241], v[240:241], 0, v[244:245]
	v_lshl_add_u64 v[242:243], v[242:243], 0, v[244:245]
	global_load_dword v229, v[240:241], off
	global_load_dword v237, v[242:243], off
	s_waitcnt vmcnt(20)
	v_mov_b32_e32 v122, v116
	v_mov_b32_e32 v123, v116

; template <class Epi, class Sched, bool ALIGN_EPI = false, bool SP2 = false>
; __device__ __forceinline__ void gemm_phase(PG8_LAS unsigned char* lds, const Gemm g, const Sched& S, const Epi& E, const int tid_arg) {
;     ...
;         const bool has_next = S.next(ui + 1, nxt);
;         const char* nA = has_next ? (const char*)g.A + (size_t)nxt.pm * tstep : cA; const char* nB = has_next ? (const char*)g.Bt + (size_t)nxt.pn * tstep : cB;
;         for (int t = 0; t < nt; t += 2) {
;             const bool last = (t == nt - 2);
;             const char* a1 = cA + (size_t)(t + 1) * kstep;
;             const char* a2 = last ? nA : cA + (size_t)(t + 2) * kstep; const char* b2 = last ? nB : cB + (size_t)(t + 2) * kstep;
;             const char* a3 = a2 + kstep; const char* b3 = b2 + kstep;
;     ...
; #pragma unroll
;         for (int a = 0; a < 2; ++a)
; #pragma unroll
;             for (int b = 0; b < 2; ++b)
; #pragma unroll
;                 for (int m = 0; m < 4; ++m)
; #pragma unroll
;                     for (int n = 0; n < 2; ++n) acc[a][b][m][n] = (f32x4){0.f, 0.f, 0.f, 0.f};
;         cur = nxt; cA = nA; cB = nB; ++ui;
.LBB0_763:
	s_ashr_i32 s27, s26, 31
	s_lshl_b64 s[28:29], s[26:27], 19
	s_add_u32 s28, s3, s28
	s_addc_u32 s29, s6, s29
	s_and_b64 s[30:31], s[10:11], exec
	s_cselect_b32 s27, s29, s5
	s_cselect_b32 s48, s28, s4
	s_ashr_i32 s25, s24, 31
	s_lshl_b64 s[30:31], s[24:25], 19
	s_add_u32 s30, s7, s30
	s_addc_u32 s31, s38, s31
	s_and_b64 s[36:37], s[10:11], exec
	s_cselect_b32 s25, s31, s35
	s_cselect_b32 s49, s30, s34
	s_add_u32 s4, s4, 0x40080
	s_addc_u32 s5, s5, 0
	s_add_u32 s50, s34, 0x100
	v_mov_b32_e32 v4, 0
	s_addc_u32 s51, s35, 0
	s_mov_b32 s52, -2
	v_mov_b32_e32 v5, v4
	v_mov_b32_e32 v6, v4
	v_mov_b32_e32 v7, v4
	v_mov_b32_e32 v8, v4
	v_mov_b32_e32 v9, v4
	v_mov_b32_e32 v10, v4
	v_mov_b32_e32 v11, v4
	v_mov_b32_e32 v20, v4
	v_mov_b32_e32 v21, v4
	v_mov_b32_e32 v22, v4
	v_mov_b32_e32 v23, v4
	v_mov_b32_e32 v24, v4
	v_mov_b32_e32 v25, v4
	v_mov_b32_e32 v26, v4
	v_mov_b32_e32 v27, v4
	v_mov_b32_e32 v36, v4
	v_mov_b32_e32 v37, v4
	v_mov_b32_e32 v38, v4
	v_mov_b32_e32 v39, v4
	v_mov_b32_e32 v40, v4
	v_mov_b32_e32 v41, v4
	v_mov_b32_e32 v42, v4
	v_mov_b32_e32 v43, v4
	v_mov_b32_e32 v52, v4
	v_mov_b32_e32 v53, v4
	v_mov_b32_e32 v54, v4
	v_mov_b32_e32 v55, v4
	v_mov_b32_e32 v56, v4
	v_mov_b32_e32 v57, v4
	v_mov_b32_e32 v58, v4
	v_mov_b32_e32 v59, v4
	v_mov_b32_e32 v12, v4
	v_mov_b32_e32 v13, v4
	v_mov_b32_e32 v14, v4
	v_mov_b32_e32 v15, v4
	v_mov_b32_e32 v16, v4
	v_mov_b32_e32 v17, v4
	v_mov_b32_e32 v18, v4
	v_mov_b32_e32 v19, v4
	v_mov_b32_e32 v28, v4
	v_mov_b32_e32 v29, v4
	v_mov_b32_e32 v30, v4
	v_mov_b32_e32 v31, v4
	v_mov_b32_e32 v32, v4
	v_mov_b32_e32 v33, v4
	v_mov_b32_e32 v34, v4
	v_mov_b32_e32 v35, v4
	v_mov_b32_e32 v44, v4
	v_mov_b32_e32 v45, v4
	v_mov_b32_e32 v46, v4
	v_mov_b32_e32 v47, v4
	v_mov_b32_e32 v48, v4
	v_mov_b32_e32 v49, v4
	v_mov_b32_e32 v50, v4
	v_mov_b32_e32 v51, v4
	v_mov_b32_e32 v60, v4
	v_mov_b32_e32 v61, v4
	v_mov_b32_e32 v62, v4
	v_mov_b32_e32 v63, v4
	v_mov_b32_e32 v64, v4
	v_mov_b32_e32 v65, v4
	v_mov_b32_e32 v66, v4
	v_mov_b32_e32 v67, v4
	v_mov_b32_e32 v68, v4
	v_mov_b32_e32 v69, v4
	v_mov_b32_e32 v70, v4
	v_mov_b32_e32 v71, v4
	v_mov_b32_e32 v72, v4
	v_mov_b32_e32 v73, v4
	v_mov_b32_e32 v74, v4
	v_mov_b32_e32 v75, v4
	v_mov_b32_e32 v84, v4
	v_mov_b32_e32 v85, v4
	v_mov_b32_e32 v86, v4
	v_mov_b32_e32 v87, v4
	v_mov_b32_e32 v88, v4
	v_mov_b32_e32 v89, v4
	v_mov_b32_e32 v90, v4
	v_mov_b32_e32 v91, v4
	v_mov_b32_e32 v100, v4
	v_mov_b32_e32 v101, v4
	v_mov_b32_e32 v102, v4
	v_mov_b32_e32 v103, v4
	v_mov_b32_e32 v104, v4
	v_mov_b32_e32 v105, v4
	v_mov_b32_e32 v106, v4
	v_mov_b32_e32 v107, v4
	v_mov_b32_e32 v116, v4
	v_mov_b32_e32 v117, v4
	v_mov_b32_e32 v118, v4
	v_mov_b32_e32 v119, v4
	s_waitcnt vmcnt(0)
	v_mov_b32_e32 v120, v4
	v_mov_b32_e32 v121, v4
	v_mov_b32_e32 v122, v4
	v_mov_b32_e32 v123, v4
	v_mov_b32_e32 v76, v4
	v_mov_b32_e32 v77, v4
	v_mov_b32_e32 v78, v4
	v_mov_b32_e32 v79, v4
	v_mov_b32_e32 v80, v4
	v_mov_b32_e32 v81, v4
	v_mov_b32_e32 v82, v4
	v_mov_b32_e32 v83, v4
	v_mov_b32_e32 v92, v4
	v_mov_b32_e32 v93, v4
	v_mov_b32_e32 v94, v4
	v_mov_b32_e32 v95, v4
	v_mov_b32_e32 v96, v4
	v_mov_b32_e32 v97, v4
	v_mov_b32_e32 v98, v4
	v_mov_b32_e32 v99, v4
	v_mov_b32_e32 v108, v4
	v_mov_b32_e32 v109, v4
	v_mov_b32_e32 v110, v4
	v_mov_b32_e32 v111, v4
	v_mov_b32_e32 v112, v4
	v_mov_b32_e32 v113, v4
	v_mov_b32_e32 v114, v4
	v_mov_b32_e32 v115, v4
	v_mov_b32_e32 v124, v4
	v_mov_b32_e32 v125, v4
	v_mov_b32_e32 v126, v4
	v_mov_b32_e32 v127, v4
	v_mov_b32_e32 v128, v4
	v_mov_b32_e32 v129, v4
	v_mov_b32_e32 v130, v4
	v_mov_b32_e32 v131, v4
	s_nop 0
	s_nop 0
	s_nop 0
	s_nop 0
	s_nop 0
	s_nop 0
	s_nop 0
	s_nop 0
	s_nop 0
	s_nop 0
	s_nop 0
	s_nop 0
	s_nop 0
	s_nop 0
	s_nop 0
	s_nop 0
